# P4 residual prefetch (7/16 quads in the last K iteration) combined with first-use counted waits in P3 hook + P3/P4/P6 epilogues
# baseline (speedup 1.0000x reference)
.LBB0_795:
	s_waitcnt vmcnt(29)
	v_lshlrev_b32_e32 v184, 16, v216
	v_and_b32_e32 v185, 0xffff0000, v216
	v_lshlrev_b32_e32 v216, 16, v217
	v_and_b32_e32 v217, 0xffff0000, v217
	v_pk_add_f32 v[144:145], v[144:145], v[216:217]
	v_pk_add_f32 v[216:217], v[142:143], v[184:185]
	v_lshlrev_b32_e32 v184, 16, v218
	v_and_b32_e32 v185, 0xffff0000, v218
	v_lshlrev_b32_e32 v142, 16, v219
	v_and_b32_e32 v143, 0xffff0000, v219
	v_pk_add_f32 v[142:143], v[136:137], v[142:143]
	v_pk_add_f32 v[218:219], v[134:135], v[184:185]
	s_mov_b64 s[2:3], -1
	s_and_b64 vcc, exec, s[14:15]
	v_cvt_pk_bf16_f32 v134, v216, v217
	v_cvt_pk_bf16_f32 v135, v144, v145
	v_cvt_pk_bf16_f32 v136, v218, v219
	v_cvt_pk_bf16_f32 v137, v142, v143
	s_cbranch_vccz .LBB0_797
	s_mov_b64 s[2:3], 0

.LBB0_799:
	s_nop 1
	s_waitcnt vmcnt(29)
	v_lshlrev_b32_e32 v134, 16, v220
	v_and_b32_e32 v135, 0xffff0000, v220
	v_lshlrev_b32_e32 v136, 16, v221
	v_and_b32_e32 v137, 0xffff0000, v221
	v_pk_add_f32 v[128:129], v[128:129], v[136:137]
	v_pk_add_f32 v[134:135], v[126:127], v[134:135]
	v_lshlrev_b32_e32 v136, 16, v222
	v_and_b32_e32 v137, 0xffff0000, v222
	v_lshlrev_b32_e32 v126, 16, v223
	v_and_b32_e32 v127, 0xffff0000, v223
	v_cndmask_b32_e64 v220, 0, 1, s[14:15]
	v_pk_add_f32 v[126:127], v[124:125], v[126:127]
	v_pk_add_f32 v[136:137], v[122:123], v[136:137]
	v_cmp_ne_u32_e64 s[2:3], 1, v220
	s_andn2_b64 vcc, exec, s[14:15]
	s_mov_b64 s[26:27], -1
	v_cvt_pk_bf16_f32 v122, v134, v135
	v_cvt_pk_bf16_f32 v123, v128, v129
	v_cvt_pk_bf16_f32 v124, v136, v137
	v_cvt_pk_bf16_f32 v125, v126, v127
	s_cbranch_vccnz .LBB0_801
	s_mov_b64 s[26:27], 0

.LBB0_805:
	s_or_b64 exec, exec, s[26:27]
	s_waitcnt vmcnt(30)
	v_lshlrev_b32_e32 v124, 16, v224
	s_waitcnt lgkmcnt(0)
	v_and_b32_e32 v125, 0xffff0000, v224
	v_lshlrev_b32_e32 v126, 16, v225
	v_and_b32_e32 v127, 0xffff0000, v225
	v_pk_add_f32 v[112:113], v[112:113], v[126:127]
	v_pk_add_f32 v[124:125], v[110:111], v[124:125]
	v_lshlrev_b32_e32 v126, 16, v226
	v_and_b32_e32 v127, 0xffff0000, v226
	v_lshlrev_b32_e32 v110, 16, v227
	v_and_b32_e32 v111, 0xffff0000, v227
	v_pk_add_f32 v[110:111], v[108:109], v[110:111]
	v_pk_add_f32 v[126:127], v[106:107], v[126:127]
	s_and_b64 vcc, exec, s[2:3]
	s_mov_b64 s[26:27], -1
	v_cvt_pk_bf16_f32 v106, v124, v125
	v_cvt_pk_bf16_f32 v107, v112, v113
	v_cvt_pk_bf16_f32 v108, v126, v127
	v_cvt_pk_bf16_f32 v109, v110, v111
	s_cbranch_vccnz .LBB0_807
	s_mov_b64 s[26:27], 0

.LBB0_809:
	s_nop 1
	s_waitcnt vmcnt(30)
	v_lshlrev_b32_e32 v106, 16, v236
	v_and_b32_e32 v107, 0xffff0000, v236
	v_lshlrev_b32_e32 v108, 16, v237
	v_and_b32_e32 v109, 0xffff0000, v237
	v_pk_add_f32 v[104:105], v[104:105], v[108:109]
	v_pk_add_f32 v[106:107], v[102:103], v[106:107]
	v_lshlrev_b32_e32 v108, 16, v238
	v_and_b32_e32 v109, 0xffff0000, v238
	v_lshlrev_b32_e32 v102, 16, v239
	v_and_b32_e32 v103, 0xffff0000, v239
	v_pk_add_f32 v[102:103], v[100:101], v[102:103]
	v_pk_add_f32 v[108:109], v[98:99], v[108:109]
	s_and_b64 vcc, exec, s[2:3]
	s_mov_b64 s[26:27], -1
	v_cvt_pk_bf16_f32 v98, v106, v107
	v_cvt_pk_bf16_f32 v99, v104, v105
	v_cvt_pk_bf16_f32 v100, v108, v109
	v_cvt_pk_bf16_f32 v101, v102, v103
	s_cbranch_vccnz .LBB0_811
	s_mov_b64 s[26:27], 0

.LBB0_815:
	s_or_b64 exec, exec, s[26:27]
	s_waitcnt vmcnt(31)
	v_lshlrev_b32_e32 v98, 16, v240
	s_waitcnt lgkmcnt(0)
	v_and_b32_e32 v99, 0xffff0000, v240
	v_lshlrev_b32_e32 v100, 16, v241
	v_and_b32_e32 v101, 0xffff0000, v241
	v_pk_add_f32 v[96:97], v[96:97], v[100:101]
	v_pk_add_f32 v[98:99], v[94:95], v[98:99]
	v_lshlrev_b32_e32 v100, 16, v242
	v_and_b32_e32 v101, 0xffff0000, v242
	v_lshlrev_b32_e32 v94, 16, v243
	v_and_b32_e32 v95, 0xffff0000, v243
	v_pk_add_f32 v[94:95], v[92:93], v[94:95]
	v_pk_add_f32 v[100:101], v[90:91], v[100:101]
	s_and_b64 vcc, exec, s[2:3]
	s_mov_b64 s[26:27], -1
	v_cvt_pk_bf16_f32 v90, v98, v99
	v_cvt_pk_bf16_f32 v91, v96, v97
	v_cvt_pk_bf16_f32 v92, v100, v101
	v_cvt_pk_bf16_f32 v93, v94, v95
	s_cbranch_vccnz .LBB0_817
	s_mov_b64 s[26:27], 0

.LBB0_819:
	s_nop 1
	s_waitcnt vmcnt(31)
	v_lshlrev_b32_e32 v90, 16, v246
	v_and_b32_e32 v91, 0xffff0000, v246
	v_lshlrev_b32_e32 v92, 16, v247
	v_and_b32_e32 v93, 0xffff0000, v247
	v_pk_add_f32 v[88:89], v[88:89], v[92:93]
	v_pk_add_f32 v[90:91], v[86:87], v[90:91]
	v_lshlrev_b32_e32 v92, 16, v248
	v_and_b32_e32 v93, 0xffff0000, v248
	v_lshlrev_b32_e32 v86, 16, v249
	v_and_b32_e32 v87, 0xffff0000, v249
	v_pk_add_f32 v[86:87], v[84:85], v[86:87]
	v_pk_add_f32 v[92:93], v[82:83], v[92:93]
	s_and_b64 vcc, exec, s[2:3]
	s_mov_b64 s[26:27], -1
	v_cvt_pk_bf16_f32 v82, v90, v91
	v_cvt_pk_bf16_f32 v83, v88, v89
	v_cvt_pk_bf16_f32 v84, v92, v93
	v_cvt_pk_bf16_f32 v85, v86, v87
	s_cbranch_vccnz .LBB0_821
	s_mov_b64 s[26:27], 0

.LBB0_825:
	s_or_b64 exec, exec, s[26:27]
	s_waitcnt vmcnt(32)
	v_lshlrev_b32_e32 v82, 16, v250
	s_waitcnt lgkmcnt(0)
	v_and_b32_e32 v83, 0xffff0000, v250
	v_lshlrev_b32_e32 v84, 16, v251
	v_and_b32_e32 v85, 0xffff0000, v251
	v_pk_add_f32 v[80:81], v[80:81], v[84:85]
	v_pk_add_f32 v[82:83], v[78:79], v[82:83]
	v_lshlrev_b32_e32 v84, 16, v252
	v_and_b32_e32 v85, 0xffff0000, v252
	v_lshlrev_b32_e32 v78, 16, v253
	v_and_b32_e32 v79, 0xffff0000, v253
	v_pk_add_f32 v[78:79], v[76:77], v[78:79]
	v_pk_add_f32 v[84:85], v[74:75], v[84:85]
	s_and_b64 vcc, exec, s[2:3]
	s_mov_b64 s[26:27], -1
	v_cvt_pk_bf16_f32 v74, v82, v83
	v_cvt_pk_bf16_f32 v75, v80, v81
	v_cvt_pk_bf16_f32 v76, v84, v85
	v_cvt_pk_bf16_f32 v77, v78, v79
	s_cbranch_vccnz .LBB0_827
	s_mov_b64 s[26:27], 0
